# K-loop bodies: MFMAs re-ordered so consecutive MFMAs share one operand register (snake order)
# speedup vs baseline: 1.0051x; 1.0051x over previous
; template <class Epi, class Sched, bool ALIGN_EPI = false, bool SP2 = false>
; __device__ __forceinline__ void gemm_phase(PG8_LAS unsigned char* lds, const Gemm g, const Sched& S, const Epi& E) {
;     ...
;         if constexpr (Epi::PEEL) {
;             const char* a1 = cA + kstepA; const char* a2 = cA + 2 * kstepA; const char* b2 = cB + 2 * kstepB; const char* a3 = a2 + kstepA; const char* b3 = b2 + kstepB;
;             PG8_ITER(8);
;         }
;         for (int t = (Epi::PEEL ? 2 : 0); t < nt; t += 2) {
;             const bool last = (t == nt - 2);
;             const char* a1 = cA + (size_t)(t + 1) * kstepA;
;             const char* a2 = last ? nA : cA + (size_t)(t + 2) * kstepA; const char* b2 = last ? nB : cB + (size_t)(t + 2) * kstepB;
;             const char* a3 = a2 + kstepA; const char* b3 = b2 + kstepB;
;             PG8_ITER(8);
.LBB0_161:
	ds_read_b128 v[146:149], v142
	ds_read_b128 v[150:153], v142 offset:1024
	ds_read_b128 v[154:157], v142 offset:2048
	ds_read_b128 v[162:165], v142 offset:3072
	ds_read_b128 v[166:169], v143
	ds_read_b128 v[170:173], v143 offset:1024
	ds_read_b128 v[174:177], v143 offset:2048
	ds_read_b128 v[180:183], v143 offset:3072
	s_add_u32 s8, s0, 0x3fc000
	s_addc_u32 s9, s1, 0
	s_cmp_eq_u32 s18, 12
	s_cselect_b32 s28, s44, s8
	s_cselect_b32 s29, s27, s9
	s_cselect_b32 s42, s49, s3
	s_cselect_b32 s43, s45, s2
	s_add_u32 s24, s28, 0x400000
	s_addc_u32 s25, s29, 0
	s_mov_b32 m0, s50
	v_lshl_add_u64 v[158:159], s[0:1], 0, v[140:141]
	ds_read_b128 v[184:187], v161
	ds_read_b128 v[188:191], v161 offset:1024
	ds_read_b128 v[192:195], v161 offset:2048
	ds_read_b128 v[196:199], v161 offset:3072
	ds_read_b128 v[200:203], v161 offset:4096
	ds_read_b128 v[204:207], v161 offset:5120
	ds_read_b128 v[208:211], v161 offset:6144
	ds_read_b128 v[212:215], v161 offset:7168
	global_load_lds_dwordx4 v[158:159], off
	v_lshl_add_u64 v[158:159], s[0:1], 0, v[138:139]
	s_mov_b32 m0, s51
	s_nop 0
	global_load_lds_dwordx4 v[158:159], off
	s_waitcnt vmcnt(8)
	s_waitcnt lgkmcnt(0)
	s_barrier
	s_setprio 1
	s_waitcnt lgkmcnt(0)
	v_mfma_f32_16x16x32_bf16 v[126:129], v[146:149], v[184:187], v[126:129]
	v_mfma_f32_16x16x32_bf16 v[118:121], v[154:157], v[184:187], v[118:121]
	v_mfma_f32_16x16x32_bf16 v[102:105], v[154:157], v[192:195], v[102:105]
	v_mfma_f32_16x16x32_bf16 v[110:113], v[146:149], v[192:195], v[110:113]
	v_mfma_f32_16x16x32_bf16 v[92:95], v[146:149], v[200:203], v[92:95]
	v_mfma_f32_16x16x32_bf16 v[84:87], v[154:157], v[200:203], v[84:87]
	v_mfma_f32_16x16x32_bf16 v[68:71], v[154:157], v[208:211], v[68:71]
	v_mfma_f32_16x16x32_bf16 v[76:79], v[146:149], v[208:211], v[76:79]
	v_mfma_f32_16x16x32_bf16 v[126:129], v[150:153], v[188:191], v[126:129]
	v_mfma_f32_16x16x32_bf16 v[118:121], v[162:165], v[188:191], v[118:121]
	v_mfma_f32_16x16x32_bf16 v[102:105], v[162:165], v[196:199], v[102:105]
	v_mfma_f32_16x16x32_bf16 v[110:113], v[150:153], v[196:199], v[110:113]
	v_mfma_f32_16x16x32_bf16 v[92:95], v[150:153], v[204:207], v[92:95]
	v_mfma_f32_16x16x32_bf16 v[84:87], v[162:165], v[204:207], v[84:87]
	v_mfma_f32_16x16x32_bf16 v[68:71], v[162:165], v[212:215], v[68:71]
	v_mfma_f32_16x16x32_bf16 v[76:79], v[150:153], v[212:215], v[76:79]
	s_setprio 0
	s_setprio 1
	v_mfma_f32_16x16x32_bf16 v[122:125], v[166:169], v[184:187], v[122:125]
	v_mfma_f32_16x16x32_bf16 v[114:117], v[174:177], v[184:187], v[114:117]
	v_mfma_f32_16x16x32_bf16 v[98:101], v[174:177], v[192:195], v[98:101]
	v_mfma_f32_16x16x32_bf16 v[106:109], v[166:169], v[192:195], v[106:109]
	v_mfma_f32_16x16x32_bf16 v[88:91], v[166:169], v[200:203], v[88:91]
	v_mfma_f32_16x16x32_bf16 v[80:83], v[174:177], v[200:203], v[80:83]
	v_mfma_f32_16x16x32_bf16 v[64:67], v[174:177], v[208:211], v[64:67]
	v_mfma_f32_16x16x32_bf16 v[72:75], v[166:169], v[208:211], v[72:75]
	v_mfma_f32_16x16x32_bf16 v[122:125], v[170:173], v[188:191], v[122:125]
	v_mfma_f32_16x16x32_bf16 v[114:117], v[180:183], v[188:191], v[114:117]
	v_mfma_f32_16x16x32_bf16 v[98:101], v[180:183], v[196:199], v[98:101]
	v_mfma_f32_16x16x32_bf16 v[106:109], v[170:173], v[196:199], v[106:109]
	v_mfma_f32_16x16x32_bf16 v[88:91], v[170:173], v[204:207], v[88:91]
	v_mfma_f32_16x16x32_bf16 v[80:83], v[180:183], v[204:207], v[80:83]
	v_mfma_f32_16x16x32_bf16 v[64:67], v[180:183], v[212:215], v[64:67]
	v_mfma_f32_16x16x32_bf16 v[72:75], v[170:173], v[212:215], v[72:75]
	s_setprio 0
	s_barrier
	s_mov_b32 m0, s55
	v_lshl_add_u64 v[158:159], s[42:43], 0, v[132:133]
	s_add_u32 s8, s42, 0x40000
	ds_read_b128 v[184:187], v161 offset:16384
	ds_read_b128 v[188:191], v161 offset:17408
	ds_read_b128 v[192:195], v161 offset:18432
	ds_read_b128 v[196:199], v161 offset:19456
	ds_read_b128 v[200:203], v161 offset:20480
	ds_read_b128 v[204:207], v161 offset:21504
	ds_read_b128 v[208:211], v161 offset:22528
	ds_read_b128 v[212:215], v161 offset:23552
	global_load_lds_dwordx4 v[158:159], off
	v_lshl_add_u64 v[178:179], s[42:43], 0, v[136:137]
	s_mov_b32 m0, vcc_lo
	s_addc_u32 s9, s43, 0
	global_load_lds_dwordx4 v[178:179], off
	v_lshl_add_u64 v[216:217], s[8:9], 0, v[132:133]
	s_mov_b32 m0, vcc_hi
	s_nop 0
	global_load_lds_dwordx4 v[216:217], off
	v_lshl_add_u64 v[216:217], s[8:9], 0, v[136:137]
	s_mov_b32 m0, s56
	s_nop 0
	global_load_lds_dwordx4 v[216:217], off
	v_lshl_add_u64 v[216:217], s[28:29], 0, v[130:131]
	s_mov_b32 m0, s22
	s_nop 0
	global_load_lds_dwordx4 v[216:217], off
	v_lshl_add_u64 v[216:217], s[28:29], 0, v[134:135]
	s_mov_b32 m0, s23
	s_nop 0
	global_load_lds_dwordx4 v[216:217], off
	s_waitcnt vmcnt(8)
	s_waitcnt lgkmcnt(0)
	s_barrier
	s_setprio 1
	s_waitcnt lgkmcnt(0)
	v_mfma_f32_16x16x32_bf16 v[60:63], v[146:149], v[184:187], v[60:63]
	v_mfma_f32_16x16x32_bf16 v[52:55], v[154:157], v[184:187], v[52:55]
	v_mfma_f32_16x16x32_bf16 v[36:39], v[154:157], v[192:195], v[36:39]
	v_mfma_f32_16x16x32_bf16 v[44:47], v[146:149], v[192:195], v[44:47]
	v_mfma_f32_16x16x32_bf16 v[28:31], v[146:149], v[200:203], v[28:31]
	v_mfma_f32_16x16x32_bf16 v[20:23], v[154:157], v[200:203], v[20:23]
	v_mfma_f32_16x16x32_bf16 v[4:7], v[154:157], v[208:211], v[4:7]
	v_mfma_f32_16x16x32_bf16 v[12:15], v[146:149], v[208:211], v[12:15]
	v_mfma_f32_16x16x32_bf16 v[60:63], v[150:153], v[188:191], v[60:63]
	v_mfma_f32_16x16x32_bf16 v[52:55], v[162:165], v[188:191], v[52:55]
	v_mfma_f32_16x16x32_bf16 v[36:39], v[162:165], v[196:199], v[36:39]
	v_mfma_f32_16x16x32_bf16 v[44:47], v[150:153], v[196:199], v[44:47]
	v_mfma_f32_16x16x32_bf16 v[28:31], v[150:153], v[204:207], v[28:31]
	v_mfma_f32_16x16x32_bf16 v[20:23], v[162:165], v[204:207], v[20:23]
	v_mfma_f32_16x16x32_bf16 v[4:7], v[162:165], v[212:215], v[4:7]
	v_mfma_f32_16x16x32_bf16 v[12:15], v[150:153], v[212:215], v[12:15]
	s_setprio 0
	s_setprio 1
	v_mfma_f32_16x16x32_bf16 v[56:59], v[166:169], v[184:187], v[56:59]
	v_mfma_f32_16x16x32_bf16 v[48:51], v[174:177], v[184:187], v[48:51]
	v_mfma_f32_16x16x32_bf16 v[32:35], v[174:177], v[192:195], v[32:35]
	v_mfma_f32_16x16x32_bf16 v[40:43], v[166:169], v[192:195], v[40:43]
	v_mfma_f32_16x16x32_bf16 v[24:27], v[166:169], v[200:203], v[24:27]
	v_mfma_f32_16x16x32_bf16 v[16:19], v[174:177], v[200:203], v[16:19]
	v_mfma_f32_16x16x32_bf16 v[0:3], v[174:177], v[208:211], v[0:3]
	v_mfma_f32_16x16x32_bf16 v[8:11], v[166:169], v[208:211], v[8:11]
	v_mfma_f32_16x16x32_bf16 v[56:59], v[170:173], v[188:191], v[56:59]
	v_mfma_f32_16x16x32_bf16 v[48:51], v[180:183], v[188:191], v[48:51]
	v_mfma_f32_16x16x32_bf16 v[32:35], v[180:183], v[196:199], v[32:35]
	v_mfma_f32_16x16x32_bf16 v[40:43], v[170:173], v[196:199], v[40:43]
	v_mfma_f32_16x16x32_bf16 v[24:27], v[170:173], v[204:207], v[24:27]
	v_mfma_f32_16x16x32_bf16 v[16:19], v[180:183], v[204:207], v[16:19]
	v_mfma_f32_16x16x32_bf16 v[0:3], v[180:183], v[212:215], v[0:3]
	v_mfma_f32_16x16x32_bf16 v[8:11], v[170:173], v[212:215], v[8:11]
	s_setprio 0
	s_barrier
	ds_read_b128 v[146:149], v144
	ds_read_b128 v[150:153], v144 offset:1024
	ds_read_b128 v[154:157], v144 offset:2048
	ds_read_b128 v[162:165], v144 offset:3072
	ds_read_b128 v[166:169], v145
	ds_read_b128 v[170:173], v145 offset:1024
	ds_read_b128 v[174:177], v145 offset:2048
	ds_read_b128 v[180:183], v145 offset:3072
	s_add_u32 s8, s28, 0x4000
	s_addc_u32 s9, s29, 0
	s_mov_b32 m0, s39
	v_lshl_add_u64 v[216:217], s[8:9], 0, v[130:131]
	ds_read_b128 v[184:187], v161 offset:32768
	ds_read_b128 v[188:191], v161 offset:33792
	ds_read_b128 v[192:195], v161 offset:34816
	ds_read_b128 v[196:199], v161 offset:35840
	ds_read_b128 v[200:203], v161 offset:36864
	ds_read_b128 v[204:207], v161 offset:37888
	ds_read_b128 v[208:211], v161 offset:38912
	ds_read_b128 v[212:215], v161 offset:39936
	global_load_lds_dwordx4 v[216:217], off
	v_lshl_add_u64 v[216:217], s[8:9], 0, v[134:135]
	s_mov_b32 m0, s52
	s_nop 0
	global_load_lds_dwordx4 v[216:217], off
	s_waitcnt vmcnt(8)
	s_waitcnt lgkmcnt(0)
	s_barrier
	s_setprio 1
	s_waitcnt lgkmcnt(0)
	v_mfma_f32_16x16x32_bf16 v[126:129], v[146:149], v[184:187], v[126:129]
	v_mfma_f32_16x16x32_bf16 v[118:121], v[154:157], v[184:187], v[118:121]
	v_mfma_f32_16x16x32_bf16 v[102:105], v[154:157], v[192:195], v[102:105]
	v_mfma_f32_16x16x32_bf16 v[110:113], v[146:149], v[192:195], v[110:113]
	v_mfma_f32_16x16x32_bf16 v[92:95], v[146:149], v[200:203], v[92:95]
	v_mfma_f32_16x16x32_bf16 v[84:87], v[154:157], v[200:203], v[84:87]
	v_mfma_f32_16x16x32_bf16 v[68:71], v[154:157], v[208:211], v[68:71]
	v_mfma_f32_16x16x32_bf16 v[76:79], v[146:149], v[208:211], v[76:79]
	v_mfma_f32_16x16x32_bf16 v[126:129], v[150:153], v[188:191], v[126:129]
	v_mfma_f32_16x16x32_bf16 v[118:121], v[162:165], v[188:191], v[118:121]
	v_mfma_f32_16x16x32_bf16 v[102:105], v[162:165], v[196:199], v[102:105]
	v_mfma_f32_16x16x32_bf16 v[110:113], v[150:153], v[196:199], v[110:113]
	v_mfma_f32_16x16x32_bf16 v[92:95], v[150:153], v[204:207], v[92:95]
	v_mfma_f32_16x16x32_bf16 v[84:87], v[162:165], v[204:207], v[84:87]
	v_mfma_f32_16x16x32_bf16 v[68:71], v[162:165], v[212:215], v[68:71]
	v_mfma_f32_16x16x32_bf16 v[76:79], v[150:153], v[212:215], v[76:79]
	s_setprio 0
	s_setprio 1
	v_mfma_f32_16x16x32_bf16 v[122:125], v[166:169], v[184:187], v[122:125]
	v_mfma_f32_16x16x32_bf16 v[114:117], v[174:177], v[184:187], v[114:117]
	v_mfma_f32_16x16x32_bf16 v[98:101], v[174:177], v[192:195], v[98:101]
	v_mfma_f32_16x16x32_bf16 v[106:109], v[166:169], v[192:195], v[106:109]
	v_mfma_f32_16x16x32_bf16 v[88:91], v[166:169], v[200:203], v[88:91]
	v_mfma_f32_16x16x32_bf16 v[80:83], v[174:177], v[200:203], v[80:83]
	v_mfma_f32_16x16x32_bf16 v[64:67], v[174:177], v[208:211], v[64:67]
	v_mfma_f32_16x16x32_bf16 v[72:75], v[166:169], v[208:211], v[72:75]
	v_mfma_f32_16x16x32_bf16 v[122:125], v[170:173], v[188:191], v[122:125]
	v_mfma_f32_16x16x32_bf16 v[114:117], v[180:183], v[188:191], v[114:117]
	v_mfma_f32_16x16x32_bf16 v[98:101], v[180:183], v[196:199], v[98:101]
	v_mfma_f32_16x16x32_bf16 v[106:109], v[170:173], v[196:199], v[106:109]
	v_mfma_f32_16x16x32_bf16 v[88:91], v[170:173], v[204:207], v[88:91]
	v_mfma_f32_16x16x32_bf16 v[80:83], v[180:183], v[204:207], v[80:83]
	v_mfma_f32_16x16x32_bf16 v[64:67], v[180:183], v[212:215], v[64:67]
	v_mfma_f32_16x16x32_bf16 v[72:75], v[170:173], v[212:215], v[72:75]
	s_setprio 0
	s_barrier
; #define PG8_BAR __builtin_amdgcn_s_barrier()
; template <class Epi, class Sched, bool ALIGN_EPI = false, bool SP2 = false>
; __device__ __forceinline__ void gemm_phase(PG8_LAS unsigned char* lds, const Gemm g, const Sched& S, const Epi& E) {
;     ...
;         if constexpr (Epi::PEEL) {
;             const char* a1 = cA + kstepA; const char* a2 = cA + 2 * kstepA; const char* b2 = cB + 2 * kstepB; const char* a3 = a2 + kstepA; const char* b3 = b2 + kstepB;
;             PG8_ITER(8);
;         }
;         for (int t = (Epi::PEEL ? 2 : 0); t < nt; t += 2) {
;             const bool last = (t == nt - 2);
;             const char* a1 = cA + (size_t)(t + 1) * kstepA;
;             const char* a2 = last ? nA : cA + (size_t)(t + 2) * kstepA; const char* b2 = last ? nB : cB + (size_t)(t + 2) * kstepB;
;             const char* a3 = a2 + kstepA; const char* b3 = b2 + kstepB;
;             PG8_ITER(8);
;         }
;     ...
;         if constexpr (ALIGN_EPI) { if (wr == 0) PG8_BAR; }
	s_mov_b32 m0, s30
	v_lshl_add_u64 v[158:159], v[158:159], 0, s[36:37]
	s_add_u32 s8, s42, 0x40080
	ds_read_b128 v[184:187], v161 offset:49152
	ds_read_b128 v[188:191], v161 offset:50176
	ds_read_b128 v[192:195], v161 offset:51200
	ds_read_b128 v[196:199], v161 offset:52224
	ds_read_b128 v[200:203], v161 offset:53248
	ds_read_b128 v[204:207], v161 offset:54272
	ds_read_b128 v[208:211], v161 offset:55296
	ds_read_b128 v[212:215], v161 offset:56320
	global_load_lds_dwordx4 v[158:159], off
	v_lshl_add_u64 v[158:159], v[178:179], 0, s[36:37]
	s_mov_b32 m0, s31
	s_addc_u32 s9, s43, 0
	global_load_lds_dwordx4 v[158:159], off
	v_lshl_add_u64 v[158:159], s[8:9], 0, v[132:133]
	s_mov_b32 m0, s57
	s_nop 0
	global_load_lds_dwordx4 v[158:159], off
	v_lshl_add_u64 v[158:159], s[8:9], 0, v[136:137]
	s_mov_b32 m0, s96
	s_nop 0
	global_load_lds_dwordx4 v[158:159], off
	v_lshl_add_u64 v[158:159], s[24:25], 0, v[130:131]
	s_mov_b32 m0, s11
	s_nop 0
	global_load_lds_dwordx4 v[158:159], off
	v_lshl_add_u64 v[158:159], s[24:25], 0, v[134:135]
	s_mov_b32 m0, s19
	s_nop 0
	global_load_lds_dwordx4 v[158:159], off
	s_waitcnt vmcnt(8)
	s_waitcnt lgkmcnt(0)
	s_barrier
	s_setprio 1
	s_waitcnt lgkmcnt(0)
	v_mfma_f32_16x16x32_bf16 v[60:63], v[146:149], v[184:187], v[60:63]
	v_mfma_f32_16x16x32_bf16 v[52:55], v[154:157], v[184:187], v[52:55]
	v_mfma_f32_16x16x32_bf16 v[36:39], v[154:157], v[192:195], v[36:39]
	v_mfma_f32_16x16x32_bf16 v[44:47], v[146:149], v[192:195], v[44:47]
	v_mfma_f32_16x16x32_bf16 v[28:31], v[146:149], v[200:203], v[28:31]
	v_mfma_f32_16x16x32_bf16 v[20:23], v[154:157], v[200:203], v[20:23]
	v_mfma_f32_16x16x32_bf16 v[4:7], v[154:157], v[208:211], v[4:7]
	v_mfma_f32_16x16x32_bf16 v[12:15], v[146:149], v[208:211], v[12:15]
	v_mfma_f32_16x16x32_bf16 v[60:63], v[150:153], v[188:191], v[60:63]
	v_mfma_f32_16x16x32_bf16 v[52:55], v[162:165], v[188:191], v[52:55]
	v_mfma_f32_16x16x32_bf16 v[36:39], v[162:165], v[196:199], v[36:39]
	v_mfma_f32_16x16x32_bf16 v[44:47], v[150:153], v[196:199], v[44:47]
	v_mfma_f32_16x16x32_bf16 v[28:31], v[150:153], v[204:207], v[28:31]
	v_mfma_f32_16x16x32_bf16 v[20:23], v[162:165], v[204:207], v[20:23]
	v_mfma_f32_16x16x32_bf16 v[4:7], v[162:165], v[212:215], v[4:7]
	v_mfma_f32_16x16x32_bf16 v[12:15], v[150:153], v[212:215], v[12:15]
	s_setprio 0
	s_setprio 1
	v_mfma_f32_16x16x32_bf16 v[56:59], v[166:169], v[184:187], v[56:59]
	v_mfma_f32_16x16x32_bf16 v[48:51], v[174:177], v[184:187], v[48:51]
	v_mfma_f32_16x16x32_bf16 v[32:35], v[174:177], v[192:195], v[32:35]
	v_mfma_f32_16x16x32_bf16 v[40:43], v[166:169], v[192:195], v[40:43]
	v_mfma_f32_16x16x32_bf16 v[24:27], v[166:169], v[200:203], v[24:27]
	v_mfma_f32_16x16x32_bf16 v[16:19], v[174:177], v[200:203], v[16:19]
	v_mfma_f32_16x16x32_bf16 v[0:3], v[174:177], v[208:211], v[0:3]
	v_mfma_f32_16x16x32_bf16 v[8:11], v[166:169], v[208:211], v[8:11]
	v_mfma_f32_16x16x32_bf16 v[56:59], v[170:173], v[188:191], v[56:59]
	v_mfma_f32_16x16x32_bf16 v[48:51], v[180:183], v[188:191], v[48:51]
	v_mfma_f32_16x16x32_bf16 v[32:35], v[180:183], v[196:199], v[32:35]
	v_mfma_f32_16x16x32_bf16 v[40:43], v[170:173], v[196:199], v[40:43]
	v_mfma_f32_16x16x32_bf16 v[24:27], v[170:173], v[204:207], v[24:27]
	v_mfma_f32_16x16x32_bf16 v[16:19], v[180:183], v[204:207], v[16:19]
	v_mfma_f32_16x16x32_bf16 v[0:3], v[180:183], v[212:215], v[0:3]
	v_mfma_f32_16x16x32_bf16 v[8:11], v[170:173], v[212:215], v[8:11]
	s_setprio 0
	s_barrier
	s_add_i32 s18, s18, 2
	s_add_u32 s3, s3, 0x100
	s_addc_u32 s2, s2, 0
	s_add_u32 s0, s0, 0x800000
	s_addc_u32 s1, s1, 0
	s_cmp_gt_u32 s18, 13
	s_cbranch_scc0 .LBB0_161
	v_readlane_b32 s0, v255, 45
	v_readlane_b32 s1, v255, 46
	s_and_b64 vcc, exec, s[0:1]
	s_cbranch_vccz .LBB0_164
	s_barrier

; template <class Epi, class Sched, bool ALIGN_EPI = false, bool SP2 = false>
; __device__ __forceinline__ void gemm_phase(PG8_LAS unsigned char* lds, const Gemm g, const Sched& S, const Epi& E) {
;     ...
;         if constexpr (Epi::PEEL) {
;             const char* a1 = cA + kstepA; const char* a2 = cA + 2 * kstepA; const char* b2 = cB + 2 * kstepB; const char* a3 = a2 + kstepA; const char* b3 = b2 + kstepB;
;             PG8_ITER(8);
;         }
;         for (int t = (Epi::PEEL ? 2 : 0); t < nt; t += 2) {
;             const bool last = (t == nt - 2);
;             const char* a1 = cA + (size_t)(t + 1) * kstepA;
;             const char* a2 = last ? nA : cA + (size_t)(t + 2) * kstepA; const char* b2 = last ? nB : cB + (size_t)(t + 2) * kstepB;
;             const char* a3 = a2 + kstepA; const char* b3 = b2 + kstepB;
;             PG8_ITER(8);
.LBB0_250:
	ds_read_b128 v[146:149], v130
	ds_read_b128 v[152:155], v130 offset:1024
	ds_read_b128 v[156:159], v130 offset:2048
	ds_read_b128 v[160:163], v130 offset:3072
	ds_read_b128 v[164:167], v131
	ds_read_b128 v[168:171], v131 offset:1024
	ds_read_b128 v[172:175], v131 offset:2048
	ds_read_b128 v[180:183], v131 offset:3072
	s_add_u32 s16, s24, 0x3fc000
	s_addc_u32 s17, s25, 0
	s_cmp_eq_u32 s18, 12
	s_cselect_b32 s28, s47, s16
	s_cselect_b32 s29, s27, s17
	s_cselect_b32 s44, s54, s3
	s_cselect_b32 s45, s49, s2
	s_add_u32 s42, s28, 0x400000
	s_addc_u32 s43, s29, 0
	s_mov_b32 m0, s55
	v_lshl_add_u64 v[176:177], s[24:25], 0, v[144:145]
	ds_read_b128 v[184:187], v151
	ds_read_b128 v[188:191], v151 offset:1024
	ds_read_b128 v[192:195], v151 offset:2048
	ds_read_b128 v[196:199], v151 offset:3072
	ds_read_b128 v[200:203], v151 offset:4096
	ds_read_b128 v[204:207], v151 offset:5120
	ds_read_b128 v[208:211], v151 offset:6144
	ds_read_b128 v[212:215], v151 offset:7168
	global_load_lds_dwordx4 v[176:177], off
	v_lshl_add_u64 v[176:177], s[24:25], 0, v[142:143]
	s_mov_b32 m0, s98
	s_nop 0
	global_load_lds_dwordx4 v[176:177], off
	s_waitcnt vmcnt(8)
	s_waitcnt lgkmcnt(0)
	s_barrier
	s_setprio 1
	s_waitcnt lgkmcnt(0)
	v_mfma_f32_16x16x32_bf16 v[118:121], v[146:149], v[184:187], v[118:121]
	v_mfma_f32_16x16x32_bf16 v[114:117], v[156:159], v[184:187], v[114:117]
	v_mfma_f32_16x16x32_bf16 v[98:101], v[156:159], v[192:195], v[98:101]
	v_mfma_f32_16x16x32_bf16 v[102:105], v[146:149], v[192:195], v[102:105]
	v_mfma_f32_16x16x32_bf16 v[84:87], v[146:149], v[200:203], v[84:87]
	v_mfma_f32_16x16x32_bf16 v[80:83], v[156:159], v[200:203], v[80:83]
	v_mfma_f32_16x16x32_bf16 v[64:67], v[156:159], v[208:211], v[64:67]
	v_mfma_f32_16x16x32_bf16 v[68:71], v[146:149], v[208:211], v[68:71]
	v_mfma_f32_16x16x32_bf16 v[118:121], v[152:155], v[188:191], v[118:121]
	v_mfma_f32_16x16x32_bf16 v[114:117], v[160:163], v[188:191], v[114:117]
	v_mfma_f32_16x16x32_bf16 v[98:101], v[160:163], v[196:199], v[98:101]
	v_mfma_f32_16x16x32_bf16 v[102:105], v[152:155], v[196:199], v[102:105]
	v_mfma_f32_16x16x32_bf16 v[84:87], v[152:155], v[204:207], v[84:87]
	v_mfma_f32_16x16x32_bf16 v[80:83], v[160:163], v[204:207], v[80:83]
	v_mfma_f32_16x16x32_bf16 v[64:67], v[160:163], v[212:215], v[64:67]
	v_mfma_f32_16x16x32_bf16 v[68:71], v[152:155], v[212:215], v[68:71]
	s_setprio 0
	s_setprio 1
	v_mfma_f32_16x16x32_bf16 v[126:129], v[164:167], v[184:187], v[126:129]
	v_mfma_f32_16x16x32_bf16 v[122:125], v[172:175], v[184:187], v[122:125]
	v_mfma_f32_16x16x32_bf16 v[106:109], v[172:175], v[192:195], v[106:109]
	v_mfma_f32_16x16x32_bf16 v[110:113], v[164:167], v[192:195], v[110:113]
	v_mfma_f32_16x16x32_bf16 v[92:95], v[164:167], v[200:203], v[92:95]
	v_mfma_f32_16x16x32_bf16 v[88:91], v[172:175], v[200:203], v[88:91]
	v_mfma_f32_16x16x32_bf16 v[72:75], v[172:175], v[208:211], v[72:75]
	v_mfma_f32_16x16x32_bf16 v[76:79], v[164:167], v[208:211], v[76:79]
	v_mfma_f32_16x16x32_bf16 v[126:129], v[168:171], v[188:191], v[126:129]
	v_mfma_f32_16x16x32_bf16 v[122:125], v[180:183], v[188:191], v[122:125]
	v_mfma_f32_16x16x32_bf16 v[106:109], v[180:183], v[196:199], v[106:109]
	v_mfma_f32_16x16x32_bf16 v[110:113], v[168:171], v[196:199], v[110:113]
	v_mfma_f32_16x16x32_bf16 v[92:95], v[168:171], v[204:207], v[92:95]
	v_mfma_f32_16x16x32_bf16 v[88:91], v[180:183], v[204:207], v[88:91]
	v_mfma_f32_16x16x32_bf16 v[72:75], v[180:183], v[212:215], v[72:75]
	v_mfma_f32_16x16x32_bf16 v[76:79], v[168:171], v[212:215], v[76:79]
	s_setprio 0
	s_barrier
	s_mov_b32 m0, s99
	v_lshl_add_u64 v[176:177], s[44:45], 0, v[136:137]
	s_add_u32 s16, s44, 0x40000
	ds_read_b128 v[184:187], v151 offset:16384
	ds_read_b128 v[188:191], v151 offset:17408
	ds_read_b128 v[192:195], v151 offset:18432
	ds_read_b128 v[196:199], v151 offset:19456
	ds_read_b128 v[200:203], v151 offset:20480
	ds_read_b128 v[204:207], v151 offset:21504
	ds_read_b128 v[208:211], v151 offset:22528
	ds_read_b128 v[212:215], v151 offset:23552
	global_load_lds_dwordx4 v[176:177], off
	v_lshl_add_u64 v[178:179], s[44:45], 0, v[140:141]
	s_mov_b32 m0, vcc_lo
	s_addc_u32 s17, s45, 0
	global_load_lds_dwordx4 v[178:179], off
	v_lshl_add_u64 v[216:217], s[16:17], 0, v[136:137]
	s_mov_b32 m0, vcc_hi
	s_nop 0
	global_load_lds_dwordx4 v[216:217], off
	v_lshl_add_u64 v[216:217], s[16:17], 0, v[140:141]
	s_mov_b32 m0, s30
	s_nop 0
	global_load_lds_dwordx4 v[216:217], off
	v_lshl_add_u64 v[216:217], s[28:29], 0, v[134:135]
	s_mov_b32 m0, s22
	s_nop 0
	global_load_lds_dwordx4 v[216:217], off
	v_lshl_add_u64 v[216:217], s[28:29], 0, v[138:139]
	s_mov_b32 m0, s23
	s_nop 0
	global_load_lds_dwordx4 v[216:217], off
	s_waitcnt vmcnt(8)
	s_waitcnt lgkmcnt(0)
	s_barrier
	s_setprio 1
	s_waitcnt lgkmcnt(0)
	v_mfma_f32_16x16x32_bf16 v[52:55], v[146:149], v[184:187], v[52:55]
	v_mfma_f32_16x16x32_bf16 v[48:51], v[156:159], v[184:187], v[48:51]
	v_mfma_f32_16x16x32_bf16 v[32:35], v[156:159], v[192:195], v[32:35]
	v_mfma_f32_16x16x32_bf16 v[36:39], v[146:149], v[192:195], v[36:39]
	v_mfma_f32_16x16x32_bf16 v[20:23], v[146:149], v[200:203], v[20:23]
	v_mfma_f32_16x16x32_bf16 v[16:19], v[156:159], v[200:203], v[16:19]
	v_mfma_f32_16x16x32_bf16 v[0:3], v[156:159], v[208:211], v[0:3]
	v_mfma_f32_16x16x32_bf16 v[4:7], v[146:149], v[208:211], v[4:7]
	v_mfma_f32_16x16x32_bf16 v[52:55], v[152:155], v[188:191], v[52:55]
	v_mfma_f32_16x16x32_bf16 v[48:51], v[160:163], v[188:191], v[48:51]
	v_mfma_f32_16x16x32_bf16 v[32:35], v[160:163], v[196:199], v[32:35]
	v_mfma_f32_16x16x32_bf16 v[36:39], v[152:155], v[196:199], v[36:39]
	v_mfma_f32_16x16x32_bf16 v[20:23], v[152:155], v[204:207], v[20:23]
	v_mfma_f32_16x16x32_bf16 v[16:19], v[160:163], v[204:207], v[16:19]
	v_mfma_f32_16x16x32_bf16 v[0:3], v[160:163], v[212:215], v[0:3]
	v_mfma_f32_16x16x32_bf16 v[4:7], v[152:155], v[212:215], v[4:7]
	s_setprio 0
	s_setprio 1
	v_mfma_f32_16x16x32_bf16 v[60:63], v[164:167], v[184:187], v[60:63]
	v_mfma_f32_16x16x32_bf16 v[56:59], v[172:175], v[184:187], v[56:59]
	v_mfma_f32_16x16x32_bf16 v[40:43], v[172:175], v[192:195], v[40:43]
	v_mfma_f32_16x16x32_bf16 v[44:47], v[164:167], v[192:195], v[44:47]
	v_mfma_f32_16x16x32_bf16 v[28:31], v[164:167], v[200:203], v[28:31]
	v_mfma_f32_16x16x32_bf16 v[24:27], v[172:175], v[200:203], v[24:27]
	v_mfma_f32_16x16x32_bf16 v[8:11], v[172:175], v[208:211], v[8:11]
	v_mfma_f32_16x16x32_bf16 v[12:15], v[164:167], v[208:211], v[12:15]
	v_mfma_f32_16x16x32_bf16 v[60:63], v[168:171], v[188:191], v[60:63]
	v_mfma_f32_16x16x32_bf16 v[56:59], v[180:183], v[188:191], v[56:59]
	v_mfma_f32_16x16x32_bf16 v[40:43], v[180:183], v[196:199], v[40:43]
	v_mfma_f32_16x16x32_bf16 v[44:47], v[168:171], v[196:199], v[44:47]
	v_mfma_f32_16x16x32_bf16 v[28:31], v[168:171], v[204:207], v[28:31]
	v_mfma_f32_16x16x32_bf16 v[24:27], v[180:183], v[204:207], v[24:27]
	v_mfma_f32_16x16x32_bf16 v[8:11], v[180:183], v[212:215], v[8:11]
	v_mfma_f32_16x16x32_bf16 v[12:15], v[168:171], v[212:215], v[12:15]
	s_setprio 0
	s_barrier
	ds_read_b128 v[146:149], v132
	ds_read_b128 v[152:155], v132 offset:1024
	ds_read_b128 v[156:159], v132 offset:2048
	ds_read_b128 v[160:163], v132 offset:3072
	ds_read_b128 v[164:167], v133
	ds_read_b128 v[168:171], v133 offset:1024
	ds_read_b128 v[172:175], v133 offset:2048
	ds_read_b128 v[180:183], v133 offset:3072
	s_add_u32 s16, s28, 0x4000
	s_addc_u32 s17, s29, 0
	s_mov_b32 m0, s39
	v_lshl_add_u64 v[216:217], s[16:17], 0, v[134:135]
	ds_read_b128 v[184:187], v151 offset:32768
	ds_read_b128 v[188:191], v151 offset:33792
	ds_read_b128 v[192:195], v151 offset:34816
	ds_read_b128 v[196:199], v151 offset:35840
	ds_read_b128 v[200:203], v151 offset:36864
	ds_read_b128 v[204:207], v151 offset:37888
	ds_read_b128 v[208:211], v151 offset:38912
	ds_read_b128 v[212:215], v151 offset:39936
	global_load_lds_dwordx4 v[216:217], off
	v_lshl_add_u64 v[216:217], s[16:17], 0, v[138:139]
	s_mov_b32 m0, s56
	s_nop 0
	global_load_lds_dwordx4 v[216:217], off
	s_waitcnt vmcnt(8)
	s_waitcnt lgkmcnt(0)
	s_barrier
	s_setprio 1
	s_waitcnt lgkmcnt(0)
	v_mfma_f32_16x16x32_bf16 v[118:121], v[146:149], v[184:187], v[118:121]
	v_mfma_f32_16x16x32_bf16 v[114:117], v[156:159], v[184:187], v[114:117]
	v_mfma_f32_16x16x32_bf16 v[98:101], v[156:159], v[192:195], v[98:101]
	v_mfma_f32_16x16x32_bf16 v[102:105], v[146:149], v[192:195], v[102:105]
	v_mfma_f32_16x16x32_bf16 v[84:87], v[146:149], v[200:203], v[84:87]
	v_mfma_f32_16x16x32_bf16 v[80:83], v[156:159], v[200:203], v[80:83]
	v_mfma_f32_16x16x32_bf16 v[64:67], v[156:159], v[208:211], v[64:67]
	v_mfma_f32_16x16x32_bf16 v[68:71], v[146:149], v[208:211], v[68:71]
	v_mfma_f32_16x16x32_bf16 v[118:121], v[152:155], v[188:191], v[118:121]
	v_mfma_f32_16x16x32_bf16 v[114:117], v[160:163], v[188:191], v[114:117]
	v_mfma_f32_16x16x32_bf16 v[98:101], v[160:163], v[196:199], v[98:101]
	v_mfma_f32_16x16x32_bf16 v[102:105], v[152:155], v[196:199], v[102:105]
	v_mfma_f32_16x16x32_bf16 v[84:87], v[152:155], v[204:207], v[84:87]
	v_mfma_f32_16x16x32_bf16 v[80:83], v[160:163], v[204:207], v[80:83]
	v_mfma_f32_16x16x32_bf16 v[64:67], v[160:163], v[212:215], v[64:67]
	v_mfma_f32_16x16x32_bf16 v[68:71], v[152:155], v[212:215], v[68:71]
	s_setprio 0
	s_setprio 1
	v_mfma_f32_16x16x32_bf16 v[126:129], v[164:167], v[184:187], v[126:129]
	v_mfma_f32_16x16x32_bf16 v[122:125], v[172:175], v[184:187], v[122:125]
	v_mfma_f32_16x16x32_bf16 v[106:109], v[172:175], v[192:195], v[106:109]
	v_mfma_f32_16x16x32_bf16 v[110:113], v[164:167], v[192:195], v[110:113]
	v_mfma_f32_16x16x32_bf16 v[92:95], v[164:167], v[200:203], v[92:95]
	v_mfma_f32_16x16x32_bf16 v[88:91], v[172:175], v[200:203], v[88:91]
	v_mfma_f32_16x16x32_bf16 v[72:75], v[172:175], v[208:211], v[72:75]
	v_mfma_f32_16x16x32_bf16 v[76:79], v[164:167], v[208:211], v[76:79]
	v_mfma_f32_16x16x32_bf16 v[126:129], v[168:171], v[188:191], v[126:129]
	v_mfma_f32_16x16x32_bf16 v[122:125], v[180:183], v[188:191], v[122:125]
	v_mfma_f32_16x16x32_bf16 v[106:109], v[180:183], v[196:199], v[106:109]
	v_mfma_f32_16x16x32_bf16 v[110:113], v[168:171], v[196:199], v[110:113]
	v_mfma_f32_16x16x32_bf16 v[92:95], v[168:171], v[204:207], v[92:95]
	v_mfma_f32_16x16x32_bf16 v[88:91], v[180:183], v[204:207], v[88:91]
	v_mfma_f32_16x16x32_bf16 v[72:75], v[180:183], v[212:215], v[72:75]
	v_mfma_f32_16x16x32_bf16 v[76:79], v[168:171], v[212:215], v[76:79]
	s_setprio 0
	s_barrier
; #define PG8_BAR __builtin_amdgcn_s_barrier()
; template <class Epi, class Sched, bool ALIGN_EPI = false, bool SP2 = false>
; __device__ __forceinline__ void gemm_phase(PG8_LAS unsigned char* lds, const Gemm g, const Sched& S, const Epi& E) {
;     ...
;         if constexpr (Epi::PEEL) {
;             const char* a1 = cA + kstepA; const char* a2 = cA + 2 * kstepA; const char* b2 = cB + 2 * kstepB; const char* a3 = a2 + kstepA; const char* b3 = b2 + kstepB;
;             PG8_ITER(8);
;         }
;         for (int t = (Epi::PEEL ? 2 : 0); t < nt; t += 2) {
;             const bool last = (t == nt - 2);
;             const char* a1 = cA + (size_t)(t + 1) * kstepA;
;             const char* a2 = last ? nA : cA + (size_t)(t + 2) * kstepA; const char* b2 = last ? nB : cB + (size_t)(t + 2) * kstepB;
;             const char* a3 = a2 + kstepA; const char* b3 = b2 + kstepB;
;             PG8_ITER(8);
;         }
;     ...
;         if constexpr (ALIGN_EPI) { if (wr == 0) PG8_BAR; }
	s_mov_b32 m0, s31
	v_lshl_add_u64 v[176:177], v[176:177], 0, s[36:37]
	s_add_u32 s16, s44, 0x40080
	ds_read_b128 v[184:187], v151 offset:49152
	ds_read_b128 v[188:191], v151 offset:50176
	ds_read_b128 v[192:195], v151 offset:51200
	ds_read_b128 v[196:199], v151 offset:52224
	ds_read_b128 v[200:203], v151 offset:53248
	ds_read_b128 v[204:207], v151 offset:54272
	ds_read_b128 v[208:211], v151 offset:55296
	ds_read_b128 v[212:215], v151 offset:56320
	global_load_lds_dwordx4 v[176:177], off
	v_lshl_add_u64 v[176:177], v[178:179], 0, s[36:37]
	s_mov_b32 m0, s12
	s_addc_u32 s17, s45, 0
	global_load_lds_dwordx4 v[176:177], off
	v_lshl_add_u64 v[176:177], s[16:17], 0, v[136:137]
	s_mov_b32 m0, s13
	s_nop 0
	global_load_lds_dwordx4 v[176:177], off
	v_lshl_add_u64 v[176:177], s[16:17], 0, v[140:141]
	s_mov_b32 m0, s11
	s_nop 0
	global_load_lds_dwordx4 v[176:177], off
	v_lshl_add_u64 v[176:177], s[42:43], 0, v[134:135]
	s_mov_b32 m0, s59
	s_nop 0
	global_load_lds_dwordx4 v[176:177], off
	v_lshl_add_u64 v[176:177], s[42:43], 0, v[138:139]
	s_mov_b32 m0, s96
	s_nop 0
	global_load_lds_dwordx4 v[176:177], off
	s_waitcnt vmcnt(8)
	s_waitcnt lgkmcnt(0)
	s_barrier
	s_setprio 1
	s_waitcnt lgkmcnt(0)
	v_mfma_f32_16x16x32_bf16 v[52:55], v[146:149], v[184:187], v[52:55]
	v_mfma_f32_16x16x32_bf16 v[48:51], v[156:159], v[184:187], v[48:51]
	v_mfma_f32_16x16x32_bf16 v[32:35], v[156:159], v[192:195], v[32:35]
	v_mfma_f32_16x16x32_bf16 v[36:39], v[146:149], v[192:195], v[36:39]
	v_mfma_f32_16x16x32_bf16 v[20:23], v[146:149], v[200:203], v[20:23]
	v_mfma_f32_16x16x32_bf16 v[16:19], v[156:159], v[200:203], v[16:19]
	v_mfma_f32_16x16x32_bf16 v[0:3], v[156:159], v[208:211], v[0:3]
	v_mfma_f32_16x16x32_bf16 v[4:7], v[146:149], v[208:211], v[4:7]
	v_mfma_f32_16x16x32_bf16 v[52:55], v[152:155], v[188:191], v[52:55]
	v_mfma_f32_16x16x32_bf16 v[48:51], v[160:163], v[188:191], v[48:51]
	v_mfma_f32_16x16x32_bf16 v[32:35], v[160:163], v[196:199], v[32:35]
	v_mfma_f32_16x16x32_bf16 v[36:39], v[152:155], v[196:199], v[36:39]
	v_mfma_f32_16x16x32_bf16 v[20:23], v[152:155], v[204:207], v[20:23]
	v_mfma_f32_16x16x32_bf16 v[16:19], v[160:163], v[204:207], v[16:19]
	v_mfma_f32_16x16x32_bf16 v[0:3], v[160:163], v[212:215], v[0:3]
	v_mfma_f32_16x16x32_bf16 v[4:7], v[152:155], v[212:215], v[4:7]
	s_setprio 0
	s_setprio 1
	v_mfma_f32_16x16x32_bf16 v[60:63], v[164:167], v[184:187], v[60:63]
	v_mfma_f32_16x16x32_bf16 v[56:59], v[172:175], v[184:187], v[56:59]
	v_mfma_f32_16x16x32_bf16 v[40:43], v[172:175], v[192:195], v[40:43]
	v_mfma_f32_16x16x32_bf16 v[44:47], v[164:167], v[192:195], v[44:47]
	v_mfma_f32_16x16x32_bf16 v[28:31], v[164:167], v[200:203], v[28:31]
	v_mfma_f32_16x16x32_bf16 v[24:27], v[172:175], v[200:203], v[24:27]
	v_mfma_f32_16x16x32_bf16 v[8:11], v[172:175], v[208:211], v[8:11]
	v_mfma_f32_16x16x32_bf16 v[12:15], v[164:167], v[208:211], v[12:15]
	v_mfma_f32_16x16x32_bf16 v[60:63], v[168:171], v[188:191], v[60:63]
	v_mfma_f32_16x16x32_bf16 v[56:59], v[180:183], v[188:191], v[56:59]
	v_mfma_f32_16x16x32_bf16 v[40:43], v[180:183], v[196:199], v[40:43]
	v_mfma_f32_16x16x32_bf16 v[44:47], v[168:171], v[196:199], v[44:47]
	v_mfma_f32_16x16x32_bf16 v[28:31], v[168:171], v[204:207], v[28:31]
	v_mfma_f32_16x16x32_bf16 v[24:27], v[180:183], v[204:207], v[24:27]
	v_mfma_f32_16x16x32_bf16 v[8:11], v[180:183], v[212:215], v[8:11]
	v_mfma_f32_16x16x32_bf16 v[12:15], v[168:171], v[212:215], v[12:15]
	s_setprio 0
	s_barrier
	s_add_i32 s18, s18, 2
	s_add_u32 s3, s3, 0x100
	s_addc_u32 s2, s2, 0
	s_add_u32 s24, s24, 0x800000
	s_addc_u32 s25, s25, 0
	s_cmp_gt_u32 s18, 13
	s_cbranch_scc0 .LBB0_250
	v_readlane_b32 s2, v255, 33
	v_readlane_b32 s3, v255, 34
	v_readlane_b32 s12, v255, 31
	s_and_b64 vcc, exec, s[2:3]
	v_readlane_b32 s13, v255, 32
	s_cbranch_vccz .LBB0_253
	s_barrier

; template <class Epi, class Sched, bool ALIGN_EPI = false, bool SP2 = false>
; __device__ __forceinline__ void gemm_phase(PG8_LAS unsigned char* lds, const Gemm g, const Sched& S, const Epi& E) {
;     ...
;         if constexpr (Epi::PEEL) {
;             const char* a1 = cA + kstepA; const char* a2 = cA + 2 * kstepA; const char* b2 = cB + 2 * kstepB; const char* a3 = a2 + kstepA; const char* b3 = b2 + kstepB;
;             PG8_ITER(8);
;         }
;         for (int t = (Epi::PEEL ? 2 : 0); t < nt; t += 2) {
;             const bool last = (t == nt - 2);
;             const char* a1 = cA + (size_t)(t + 1) * kstepA;
;             const char* a2 = last ? nA : cA + (size_t)(t + 2) * kstepA; const char* b2 = last ? nB : cB + (size_t)(t + 2) * kstepB;
;             const char* a3 = a2 + kstepA; const char* b3 = b2 + kstepB;
;             PG8_ITER(8);
.LBB0_345:
	s_add_i32 s10, s10, 2
	s_add_u32 s44, s42, s34
	s_addc_u32 s45, s43, s35
	s_add_i32 s18, 0, 0x10000
	s_and_b64 s[2:3], exec, s[46:47]
	s_cselect_b32 s3, s13, s59
	s_cselect_b32 s2, s12, s58
	s_add_i32 s38, 0, 0x14000
	v_add_u32_e32 v142, s18, v97
	v_add_u32_e32 v170, s38, v97
	ds_read_b128 v[122:125], v142
	ds_read_b128 v[126:129], v142 offset:1024
	ds_read_b128 v[138:141], v142 offset:2048
	ds_read_b128 v[142:145], v142 offset:3072
	ds_read_b128 v[146:149], v170
	ds_read_b128 v[150:153], v170 offset:1024
	ds_read_b128 v[154:157], v170 offset:2048
	ds_read_b128 v[170:173], v170 offset:3072
	v_lshl_add_u64 v[178:179], s[24:25], 0, v[168:169]
	s_add_i32 m0, s97, 0xc000
	ds_read_b128 v[174:177], v188
	ds_read_b128 v[180:183], v188 offset:1024
	ds_read_b128 v[184:187], v188 offset:2048
	ds_read_b128 v[190:193], v188 offset:3072
	ds_read_b128 v[194:197], v188 offset:4096
	ds_read_b128 v[198:201], v188 offset:5120
	ds_read_b128 v[202:205], v188 offset:6144
	ds_read_b128 v[206:209], v188 offset:7168
	global_load_lds_dwordx4 v[178:179], off
	v_lshl_add_u64 v[178:179], s[24:25], 0, v[166:167]
	s_add_i32 m0, s97, 0xe000
	s_nop 0
	global_load_lds_dwordx4 v[178:179], off
	s_waitcnt vmcnt(8)
	s_waitcnt lgkmcnt(0)
	s_barrier
	s_setprio 1
	s_waitcnt lgkmcnt(0)
	v_mfma_f32_16x16x32_bf16 v[134:137], v[122:125], v[174:177], v[134:137]
	v_mfma_f32_16x16x32_bf16 v[130:133], v[138:141], v[174:177], v[130:133]
	v_mfma_f32_16x16x32_bf16 v[106:109], v[138:141], v[184:187], v[106:109]
	v_mfma_f32_16x16x32_bf16 v[110:113], v[122:125], v[184:187], v[110:113]
	v_mfma_f32_16x16x32_bf16 v[92:95], v[122:125], v[194:197], v[92:95]
	v_mfma_f32_16x16x32_bf16 v[88:91], v[138:141], v[194:197], v[88:91]
	v_mfma_f32_16x16x32_bf16 v[72:75], v[138:141], v[202:205], v[72:75]
	v_mfma_f32_16x16x32_bf16 v[76:79], v[122:125], v[202:205], v[76:79]
	v_mfma_f32_16x16x32_bf16 v[134:137], v[126:129], v[180:183], v[134:137]
	v_mfma_f32_16x16x32_bf16 v[130:133], v[142:145], v[180:183], v[130:133]
	v_mfma_f32_16x16x32_bf16 v[106:109], v[142:145], v[190:193], v[106:109]
	v_mfma_f32_16x16x32_bf16 v[110:113], v[126:129], v[190:193], v[110:113]
	v_mfma_f32_16x16x32_bf16 v[92:95], v[126:129], v[198:201], v[92:95]
	v_mfma_f32_16x16x32_bf16 v[88:91], v[142:145], v[198:201], v[88:91]
	v_mfma_f32_16x16x32_bf16 v[72:75], v[142:145], v[206:209], v[72:75]
	v_mfma_f32_16x16x32_bf16 v[76:79], v[126:129], v[206:209], v[76:79]
	s_setprio 0
	s_setprio 1
	v_mfma_f32_16x16x32_bf16 v[118:121], v[146:149], v[174:177], v[118:121]
	v_mfma_f32_16x16x32_bf16 v[114:117], v[154:157], v[174:177], v[114:117]
	v_mfma_f32_16x16x32_bf16 v[98:101], v[154:157], v[184:187], v[98:101]
	v_mfma_f32_16x16x32_bf16 v[102:105], v[146:149], v[184:187], v[102:105]
	v_mfma_f32_16x16x32_bf16 v[84:87], v[146:149], v[194:197], v[84:87]
	v_mfma_f32_16x16x32_bf16 v[80:83], v[154:157], v[194:197], v[80:83]
	v_mfma_f32_16x16x32_bf16 v[64:67], v[154:157], v[202:205], v[64:67]
	v_mfma_f32_16x16x32_bf16 v[68:71], v[146:149], v[202:205], v[68:71]
	v_mfma_f32_16x16x32_bf16 v[118:121], v[150:153], v[180:183], v[118:121]
	v_mfma_f32_16x16x32_bf16 v[114:117], v[170:173], v[180:183], v[114:117]
	v_mfma_f32_16x16x32_bf16 v[98:101], v[170:173], v[190:193], v[98:101]
	v_mfma_f32_16x16x32_bf16 v[102:105], v[150:153], v[190:193], v[102:105]
	v_mfma_f32_16x16x32_bf16 v[84:87], v[150:153], v[198:201], v[84:87]
	v_mfma_f32_16x16x32_bf16 v[80:83], v[170:173], v[198:201], v[80:83]
	v_mfma_f32_16x16x32_bf16 v[64:67], v[170:173], v[206:209], v[64:67]
	v_mfma_f32_16x16x32_bf16 v[68:71], v[150:153], v[206:209], v[68:71]
	s_setprio 0
	s_barrier
	s_add_i32 s18, s18, s96
	v_lshl_add_u64 v[178:179], s[2:3], 0, v[162:163]
	s_mov_b32 m0, s18
	ds_read_b128 v[174:177], v188 offset:16384
	ds_read_b128 v[180:183], v188 offset:17408
	ds_read_b128 v[184:187], v188 offset:18432
	ds_read_b128 v[190:193], v188 offset:19456
	ds_read_b128 v[194:197], v188 offset:20480
	ds_read_b128 v[198:201], v188 offset:21504
	ds_read_b128 v[202:205], v188 offset:22528
	ds_read_b128 v[206:209], v188 offset:23552
	global_load_lds_dwordx4 v[178:179], off
	s_add_i32 m0, s18, 0x2000
	v_lshl_add_u64 v[210:211], s[2:3], 0, v[158:159]
	s_add_u32 s2, s2, s48
	s_addc_u32 s3, s3, 0
	s_add_i32 s18, s38, s96
	global_load_lds_dwordx4 v[210:211], off
	v_lshl_add_u64 v[212:213], s[2:3], 0, v[162:163]
	s_mov_b32 m0, s18
	v_lshl_add_u64 v[214:215], s[2:3], 0, v[158:159]
	global_load_lds_dwordx4 v[212:213], off
	s_add_i32 m0, s18, 0x2000
	v_lshl_add_u64 v[216:217], s[42:43], 0, v[164:165]
	global_load_lds_dwordx4 v[214:215], off
	s_mov_b32 m0, s97
	s_nop 0
	global_load_lds_dwordx4 v[216:217], off
	v_lshl_add_u64 v[216:217], s[42:43], 0, v[160:161]
	s_mov_b32 m0, s22
	s_nop 0
	global_load_lds_dwordx4 v[216:217], off
	s_waitcnt vmcnt(8)
	s_waitcnt lgkmcnt(0)
	s_barrier
	s_setprio 1
	s_waitcnt lgkmcnt(0)
	v_mfma_f32_16x16x32_bf16 v[60:63], v[122:125], v[174:177], v[60:63]
	v_mfma_f32_16x16x32_bf16 v[56:59], v[138:141], v[174:177], v[56:59]
	v_mfma_f32_16x16x32_bf16 v[40:43], v[138:141], v[184:187], v[40:43]
	v_mfma_f32_16x16x32_bf16 v[44:47], v[122:125], v[184:187], v[44:47]
	v_mfma_f32_16x16x32_bf16 v[28:31], v[122:125], v[194:197], v[28:31]
	v_mfma_f32_16x16x32_bf16 v[24:27], v[138:141], v[194:197], v[24:27]
	v_mfma_f32_16x16x32_bf16 v[8:11], v[138:141], v[202:205], v[8:11]
	v_mfma_f32_16x16x32_bf16 v[12:15], v[122:125], v[202:205], v[12:15]
	v_mfma_f32_16x16x32_bf16 v[60:63], v[126:129], v[180:183], v[60:63]
	v_mfma_f32_16x16x32_bf16 v[56:59], v[142:145], v[180:183], v[56:59]
	v_mfma_f32_16x16x32_bf16 v[40:43], v[142:145], v[190:193], v[40:43]
	v_mfma_f32_16x16x32_bf16 v[44:47], v[126:129], v[190:193], v[44:47]
	v_mfma_f32_16x16x32_bf16 v[28:31], v[126:129], v[198:201], v[28:31]
	v_mfma_f32_16x16x32_bf16 v[24:27], v[142:145], v[198:201], v[24:27]
	v_mfma_f32_16x16x32_bf16 v[8:11], v[142:145], v[206:209], v[8:11]
	v_mfma_f32_16x16x32_bf16 v[12:15], v[126:129], v[206:209], v[12:15]
	s_setprio 0
	s_setprio 1
	v_mfma_f32_16x16x32_bf16 v[52:55], v[146:149], v[174:177], v[52:55]
	v_mfma_f32_16x16x32_bf16 v[48:51], v[154:157], v[174:177], v[48:51]
	v_mfma_f32_16x16x32_bf16 v[32:35], v[154:157], v[184:187], v[32:35]
	v_mfma_f32_16x16x32_bf16 v[36:39], v[146:149], v[184:187], v[36:39]
	v_mfma_f32_16x16x32_bf16 v[20:23], v[146:149], v[194:197], v[20:23]
	v_mfma_f32_16x16x32_bf16 v[16:19], v[154:157], v[194:197], v[16:19]
	v_mfma_f32_16x16x32_bf16 v[0:3], v[154:157], v[202:205], v[0:3]
	v_mfma_f32_16x16x32_bf16 v[4:7], v[146:149], v[202:205], v[4:7]
	v_mfma_f32_16x16x32_bf16 v[52:55], v[150:153], v[180:183], v[52:55]
	v_mfma_f32_16x16x32_bf16 v[48:51], v[170:173], v[180:183], v[48:51]
	v_mfma_f32_16x16x32_bf16 v[32:35], v[170:173], v[190:193], v[32:35]
	v_mfma_f32_16x16x32_bf16 v[36:39], v[150:153], v[190:193], v[36:39]
	v_mfma_f32_16x16x32_bf16 v[20:23], v[150:153], v[198:201], v[20:23]
	v_mfma_f32_16x16x32_bf16 v[16:19], v[170:173], v[198:201], v[16:19]
	v_mfma_f32_16x16x32_bf16 v[0:3], v[170:173], v[206:209], v[0:3]
	v_mfma_f32_16x16x32_bf16 v[4:7], v[150:153], v[206:209], v[4:7]
	s_setprio 0
	s_barrier
	s_add_i32 s18, 0, 0x18000
	s_add_i32 s38, 0, 0x1c000
	v_add_u32_e32 v142, s18, v97
	v_add_u32_e32 v170, s38, v97
	ds_read_b128 v[122:125], v142
	ds_read_b128 v[126:129], v142 offset:1024
	ds_read_b128 v[138:141], v142 offset:2048
	ds_read_b128 v[142:145], v142 offset:3072
	ds_read_b128 v[146:149], v170
	ds_read_b128 v[150:153], v170 offset:1024
	ds_read_b128 v[154:157], v170 offset:2048
	ds_read_b128 v[170:173], v170 offset:3072
	s_add_u32 s2, s42, s98
	s_addc_u32 s3, s43, 0
	s_mov_b32 m0, s23
	v_lshl_add_u64 v[216:217], s[2:3], 0, v[164:165]
	ds_read_b128 v[174:177], v188 offset:32768
	ds_read_b128 v[180:183], v188 offset:33792
	ds_read_b128 v[184:187], v188 offset:34816
	ds_read_b128 v[190:193], v188 offset:35840
	ds_read_b128 v[194:197], v188 offset:36864
	ds_read_b128 v[198:201], v188 offset:37888
	ds_read_b128 v[202:205], v188 offset:38912
	ds_read_b128 v[206:209], v188 offset:39936
	global_load_lds_dwordx4 v[216:217], off
	v_lshl_add_u64 v[216:217], s[2:3], 0, v[160:161]
	s_mov_b32 m0, s19
	s_nop 0
	global_load_lds_dwordx4 v[216:217], off
	s_waitcnt vmcnt(8)
	s_waitcnt lgkmcnt(0)
	s_barrier
	s_setprio 1
	s_waitcnt lgkmcnt(0)
	v_mfma_f32_16x16x32_bf16 v[134:137], v[122:125], v[174:177], v[134:137]
	v_mfma_f32_16x16x32_bf16 v[130:133], v[138:141], v[174:177], v[130:133]
	v_mfma_f32_16x16x32_bf16 v[106:109], v[138:141], v[184:187], v[106:109]
	v_mfma_f32_16x16x32_bf16 v[110:113], v[122:125], v[184:187], v[110:113]
	v_mfma_f32_16x16x32_bf16 v[92:95], v[122:125], v[194:197], v[92:95]
	v_mfma_f32_16x16x32_bf16 v[88:91], v[138:141], v[194:197], v[88:91]
	v_mfma_f32_16x16x32_bf16 v[72:75], v[138:141], v[202:205], v[72:75]
	v_mfma_f32_16x16x32_bf16 v[76:79], v[122:125], v[202:205], v[76:79]
	v_mfma_f32_16x16x32_bf16 v[134:137], v[126:129], v[180:183], v[134:137]
	v_mfma_f32_16x16x32_bf16 v[130:133], v[142:145], v[180:183], v[130:133]
	v_mfma_f32_16x16x32_bf16 v[106:109], v[142:145], v[190:193], v[106:109]
	v_mfma_f32_16x16x32_bf16 v[110:113], v[126:129], v[190:193], v[110:113]
	v_mfma_f32_16x16x32_bf16 v[92:95], v[126:129], v[198:201], v[92:95]
	v_mfma_f32_16x16x32_bf16 v[88:91], v[142:145], v[198:201], v[88:91]
	v_mfma_f32_16x16x32_bf16 v[72:75], v[142:145], v[206:209], v[72:75]
	v_mfma_f32_16x16x32_bf16 v[76:79], v[126:129], v[206:209], v[76:79]
	s_setprio 0
	s_setprio 1
	v_mfma_f32_16x16x32_bf16 v[118:121], v[146:149], v[174:177], v[118:121]
	v_mfma_f32_16x16x32_bf16 v[114:117], v[154:157], v[174:177], v[114:117]
	v_mfma_f32_16x16x32_bf16 v[98:101], v[154:157], v[184:187], v[98:101]
	v_mfma_f32_16x16x32_bf16 v[102:105], v[146:149], v[184:187], v[102:105]
	v_mfma_f32_16x16x32_bf16 v[84:87], v[146:149], v[194:197], v[84:87]
	v_mfma_f32_16x16x32_bf16 v[80:83], v[154:157], v[194:197], v[80:83]
	v_mfma_f32_16x16x32_bf16 v[64:67], v[154:157], v[202:205], v[64:67]
	v_mfma_f32_16x16x32_bf16 v[68:71], v[146:149], v[202:205], v[68:71]
	v_mfma_f32_16x16x32_bf16 v[118:121], v[150:153], v[180:183], v[118:121]
	v_mfma_f32_16x16x32_bf16 v[114:117], v[170:173], v[180:183], v[114:117]
	v_mfma_f32_16x16x32_bf16 v[98:101], v[170:173], v[190:193], v[98:101]
	v_mfma_f32_16x16x32_bf16 v[102:105], v[150:153], v[190:193], v[102:105]
	v_mfma_f32_16x16x32_bf16 v[84:87], v[150:153], v[198:201], v[84:87]
	v_mfma_f32_16x16x32_bf16 v[80:83], v[170:173], v[198:201], v[80:83]
	v_mfma_f32_16x16x32_bf16 v[64:67], v[170:173], v[206:209], v[64:67]
	v_mfma_f32_16x16x32_bf16 v[68:71], v[150:153], v[206:209], v[68:71]
	s_setprio 0
	s_barrier
; template <class Epi, class Sched, bool ALIGN_EPI = false, bool SP2 = false>
; __device__ __forceinline__ void gemm_phase(PG8_LAS unsigned char* lds, const Gemm g, const Sched& S, const Epi& E) {
;     ...
;         if constexpr (Epi::PEEL) {
;             const char* a1 = cA + kstepA; const char* a2 = cA + 2 * kstepA; const char* b2 = cB + 2 * kstepB; const char* a3 = a2 + kstepA; const char* b3 = b2 + kstepB;
;             PG8_ITER(8);
;         }
;         for (int t = (Epi::PEEL ? 2 : 0); t < nt; t += 2) {
;             const bool last = (t == nt - 2);
;             const char* a1 = cA + (size_t)(t + 1) * kstepA;
;             const char* a2 = last ? nA : cA + (size_t)(t + 2) * kstepA; const char* b2 = last ? nB : cB + (size_t)(t + 2) * kstepB;
;             const char* a3 = a2 + kstepA; const char* b3 = b2 + kstepB;
;             PG8_ITER(8);
	s_add_i32 s2, s18, s96
	v_lshl_add_u64 v[178:179], v[178:179], 0, s[36:37]
	s_mov_b32 m0, s2
	ds_read_b128 v[174:177], v188 offset:49152
	ds_read_b128 v[180:183], v188 offset:50176
	ds_read_b128 v[184:187], v188 offset:51200
	ds_read_b128 v[190:193], v188 offset:52224
	ds_read_b128 v[194:197], v188 offset:53248
	ds_read_b128 v[198:201], v188 offset:54272
	ds_read_b128 v[202:205], v188 offset:55296
	ds_read_b128 v[206:209], v188 offset:56320
	global_load_lds_dwordx4 v[178:179], off
	v_lshl_add_u64 v[178:179], v[210:211], 0, s[36:37]
	s_add_i32 m0, s2, 0x2000
	s_add_i32 s2, s38, s96
	global_load_lds_dwordx4 v[178:179], off
	v_lshl_add_u64 v[178:179], v[212:213], 0, s[36:37]
	s_mov_b32 m0, s2
	s_nop 0
	global_load_lds_dwordx4 v[178:179], off
	v_lshl_add_u64 v[178:179], v[214:215], 0, s[36:37]
	s_add_i32 m0, s2, 0x2000
	s_nop 0
	global_load_lds_dwordx4 v[178:179], off
	v_lshl_add_u64 v[178:179], s[44:45], 0, v[164:165]
	s_mov_b32 m0, s6
	s_nop 0
	global_load_lds_dwordx4 v[178:179], off
	v_lshl_add_u64 v[178:179], s[44:45], 0, v[160:161]
	s_mov_b32 m0, s56
	s_nop 0
	global_load_lds_dwordx4 v[178:179], off
	s_waitcnt vmcnt(8)
	s_waitcnt lgkmcnt(0)
	s_barrier
	s_setprio 1
	s_waitcnt lgkmcnt(0)
	v_mfma_f32_16x16x32_bf16 v[60:63], v[122:125], v[174:177], v[60:63]
	v_mfma_f32_16x16x32_bf16 v[56:59], v[138:141], v[174:177], v[56:59]
	v_mfma_f32_16x16x32_bf16 v[40:43], v[138:141], v[184:187], v[40:43]
	v_mfma_f32_16x16x32_bf16 v[44:47], v[122:125], v[184:187], v[44:47]
	v_mfma_f32_16x16x32_bf16 v[28:31], v[122:125], v[194:197], v[28:31]
	v_mfma_f32_16x16x32_bf16 v[24:27], v[138:141], v[194:197], v[24:27]
	v_mfma_f32_16x16x32_bf16 v[8:11], v[138:141], v[202:205], v[8:11]
	v_mfma_f32_16x16x32_bf16 v[12:15], v[122:125], v[202:205], v[12:15]
	v_mfma_f32_16x16x32_bf16 v[60:63], v[126:129], v[180:183], v[60:63]
	v_mfma_f32_16x16x32_bf16 v[56:59], v[142:145], v[180:183], v[56:59]
	v_mfma_f32_16x16x32_bf16 v[40:43], v[142:145], v[190:193], v[40:43]
	v_mfma_f32_16x16x32_bf16 v[44:47], v[126:129], v[190:193], v[44:47]
	v_mfma_f32_16x16x32_bf16 v[28:31], v[126:129], v[198:201], v[28:31]
	v_mfma_f32_16x16x32_bf16 v[24:27], v[142:145], v[198:201], v[24:27]
	v_mfma_f32_16x16x32_bf16 v[8:11], v[142:145], v[206:209], v[8:11]
	v_mfma_f32_16x16x32_bf16 v[12:15], v[126:129], v[206:209], v[12:15]
	s_setprio 0
	s_setprio 1
	v_mfma_f32_16x16x32_bf16 v[52:55], v[146:149], v[174:177], v[52:55]
	v_mfma_f32_16x16x32_bf16 v[48:51], v[154:157], v[174:177], v[48:51]
	v_mfma_f32_16x16x32_bf16 v[32:35], v[154:157], v[184:187], v[32:35]
	v_mfma_f32_16x16x32_bf16 v[36:39], v[146:149], v[184:187], v[36:39]
	v_mfma_f32_16x16x32_bf16 v[20:23], v[146:149], v[194:197], v[20:23]
	v_mfma_f32_16x16x32_bf16 v[16:19], v[154:157], v[194:197], v[16:19]
	v_mfma_f32_16x16x32_bf16 v[0:3], v[154:157], v[202:205], v[0:3]
	v_mfma_f32_16x16x32_bf16 v[4:7], v[146:149], v[202:205], v[4:7]
	v_mfma_f32_16x16x32_bf16 v[52:55], v[150:153], v[180:183], v[52:55]
	v_mfma_f32_16x16x32_bf16 v[48:51], v[170:173], v[180:183], v[48:51]
	v_mfma_f32_16x16x32_bf16 v[32:35], v[170:173], v[190:193], v[32:35]
	v_mfma_f32_16x16x32_bf16 v[36:39], v[150:153], v[190:193], v[36:39]
	v_mfma_f32_16x16x32_bf16 v[20:23], v[150:153], v[198:201], v[20:23]
	v_mfma_f32_16x16x32_bf16 v[16:19], v[170:173], v[198:201], v[16:19]
	v_mfma_f32_16x16x32_bf16 v[0:3], v[170:173], v[206:209], v[0:3]
	v_mfma_f32_16x16x32_bf16 v[4:7], v[150:153], v[206:209], v[4:7]
	s_setprio 0
	s_barrier
	s_add_u32 s58, s58, 0x100
	s_addc_u32 s59, s59, 0
	s_add_u32 s24, s24, s49
	s_addc_u32 s25, s25, 0
	s_cmp_ge_u32 s10, s8
	s_cbranch_scc1 .LBB0_348

; template <class Epi, class Sched, bool ALIGN_EPI = false, bool SP2 = false>
; __device__ __forceinline__ void gemm_phase(PG8_LAS unsigned char* lds, const Gemm g, const Sched& S, const Epi& E) {
;     ...
;         if constexpr (Epi::PEEL) {
;             const char* a1 = cA + kstepA; const char* a2 = cA + 2 * kstepA; const char* b2 = cB + 2 * kstepB; const char* a3 = a2 + kstepA; const char* b3 = b2 + kstepB;
;             PG8_ITER(8);
;         }
;         for (int t = (Epi::PEEL ? 2 : 0); t < nt; t += 2) {
;             const bool last = (t == nt - 2);
;             const char* a1 = cA + (size_t)(t + 1) * kstepA;
;             const char* a2 = last ? nA : cA + (size_t)(t + 2) * kstepA; const char* b2 = last ? nB : cB + (size_t)(t + 2) * kstepB;
;             const char* a3 = a2 + kstepA; const char* b3 = b2 + kstepB;
;             PG8_ITER(8);
.LBB0_478:
	ds_read_b128 v[146:149], v142
	ds_read_b128 v[150:153], v142 offset:1024
	ds_read_b128 v[158:161], v142 offset:2048
	ds_read_b128 v[162:165], v142 offset:3072
	ds_read_b128 v[166:169], v143
	ds_read_b128 v[170:173], v143 offset:1024
	ds_read_b128 v[174:177], v143 offset:2048
	ds_read_b128 v[180:183], v143 offset:3072
	s_add_u32 s10, s0, 0x3fc000
	s_addc_u32 s11, s1, 0
	s_cmp_eq_u32 s18, 12
	s_cselect_b32 s44, s27, s10
	s_cselect_b32 s45, s25, s11
	s_cselect_b32 s42, s58, s3
	s_cselect_b32 s43, s57, s2
	s_add_u32 s34, s44, 0x400000
	s_addc_u32 s35, s45, 0
	s_mov_b32 m0, s59
	v_lshl_add_u64 v[154:155], s[0:1], 0, v[140:141]
	ds_read_b128 v[184:187], v156
	ds_read_b128 v[188:191], v156 offset:1024
	ds_read_b128 v[192:195], v156 offset:2048
	ds_read_b128 v[196:199], v156 offset:3072
	ds_read_b128 v[200:203], v156 offset:4096
	ds_read_b128 v[204:207], v156 offset:5120
	ds_read_b128 v[208:211], v156 offset:6144
	ds_read_b128 v[212:215], v156 offset:7168
	global_load_lds_dwordx4 v[154:155], off
	v_lshl_add_u64 v[154:155], s[0:1], 0, v[138:139]
	s_mov_b32 m0, s60
	s_nop 0
	global_load_lds_dwordx4 v[154:155], off
	s_waitcnt vmcnt(8)
	s_waitcnt lgkmcnt(0)
	s_barrier
	s_setprio 1
	s_waitcnt lgkmcnt(0)
	v_mfma_f32_16x16x32_bf16 v[122:125], v[146:149], v[184:187], v[122:125]
	v_mfma_f32_16x16x32_bf16 v[114:117], v[158:161], v[184:187], v[114:117]
	v_mfma_f32_16x16x32_bf16 v[98:101], v[158:161], v[192:195], v[98:101]
	v_mfma_f32_16x16x32_bf16 v[106:109], v[146:149], v[192:195], v[106:109]
	v_mfma_f32_16x16x32_bf16 v[88:91], v[146:149], v[200:203], v[88:91]
	v_mfma_f32_16x16x32_bf16 v[80:83], v[158:161], v[200:203], v[80:83]
	v_mfma_f32_16x16x32_bf16 v[60:63], v[158:161], v[208:211], v[60:63]
	v_mfma_f32_16x16x32_bf16 v[72:75], v[146:149], v[208:211], v[72:75]
	v_mfma_f32_16x16x32_bf16 v[122:125], v[150:153], v[188:191], v[122:125]
	v_mfma_f32_16x16x32_bf16 v[114:117], v[162:165], v[188:191], v[114:117]
	v_mfma_f32_16x16x32_bf16 v[98:101], v[162:165], v[196:199], v[98:101]
	v_mfma_f32_16x16x32_bf16 v[106:109], v[150:153], v[196:199], v[106:109]
	v_mfma_f32_16x16x32_bf16 v[88:91], v[150:153], v[204:207], v[88:91]
	v_mfma_f32_16x16x32_bf16 v[80:83], v[162:165], v[204:207], v[80:83]
	v_mfma_f32_16x16x32_bf16 v[60:63], v[162:165], v[212:215], v[60:63]
	v_mfma_f32_16x16x32_bf16 v[72:75], v[150:153], v[212:215], v[72:75]
	s_setprio 0
	s_setprio 1
	v_mfma_f32_16x16x32_bf16 v[126:129], v[166:169], v[184:187], v[126:129]
	v_mfma_f32_16x16x32_bf16 v[118:121], v[174:177], v[184:187], v[118:121]
	v_mfma_f32_16x16x32_bf16 v[102:105], v[174:177], v[192:195], v[102:105]
	v_mfma_f32_16x16x32_bf16 v[110:113], v[166:169], v[192:195], v[110:113]
	v_mfma_f32_16x16x32_bf16 v[92:95], v[166:169], v[200:203], v[92:95]
	v_mfma_f32_16x16x32_bf16 v[84:87], v[174:177], v[200:203], v[84:87]
	v_mfma_f32_16x16x32_bf16 v[68:71], v[174:177], v[208:211], v[68:71]
	v_mfma_f32_16x16x32_bf16 v[76:79], v[166:169], v[208:211], v[76:79]
	v_mfma_f32_16x16x32_bf16 v[126:129], v[170:173], v[188:191], v[126:129]
	v_mfma_f32_16x16x32_bf16 v[118:121], v[180:183], v[188:191], v[118:121]
	v_mfma_f32_16x16x32_bf16 v[102:105], v[180:183], v[196:199], v[102:105]
	v_mfma_f32_16x16x32_bf16 v[110:113], v[170:173], v[196:199], v[110:113]
	v_mfma_f32_16x16x32_bf16 v[92:95], v[170:173], v[204:207], v[92:95]
	v_mfma_f32_16x16x32_bf16 v[84:87], v[180:183], v[204:207], v[84:87]
	v_mfma_f32_16x16x32_bf16 v[68:71], v[180:183], v[212:215], v[68:71]
	v_mfma_f32_16x16x32_bf16 v[76:79], v[170:173], v[212:215], v[76:79]
	s_setprio 0
	s_barrier
	s_mov_b32 m0, s61
	v_lshl_add_u64 v[154:155], s[42:43], 0, v[132:133]
	s_add_u32 s10, s42, 0x40000
	ds_read_b128 v[184:187], v156 offset:16384
	ds_read_b128 v[188:191], v156 offset:17408
	ds_read_b128 v[192:195], v156 offset:18432
	ds_read_b128 v[196:199], v156 offset:19456
	ds_read_b128 v[200:203], v156 offset:20480
	ds_read_b128 v[204:207], v156 offset:21504
	ds_read_b128 v[208:211], v156 offset:22528
	ds_read_b128 v[212:215], v156 offset:23552
	global_load_lds_dwordx4 v[154:155], off
	v_lshl_add_u64 v[178:179], s[42:43], 0, v[136:137]
	s_mov_b32 m0, s96
	s_addc_u32 s11, s43, 0
	global_load_lds_dwordx4 v[178:179], off
	v_lshl_add_u64 v[216:217], s[10:11], 0, v[132:133]
	s_mov_b32 m0, s97
	s_nop 0
	global_load_lds_dwordx4 v[216:217], off
	v_lshl_add_u64 v[216:217], s[10:11], 0, v[136:137]
	s_mov_b32 m0, s98
	s_nop 0
	global_load_lds_dwordx4 v[216:217], off
	v_lshl_add_u64 v[216:217], s[44:45], 0, v[130:131]
	s_mov_b32 m0, s23
	s_nop 0
	global_load_lds_dwordx4 v[216:217], off
	v_lshl_add_u64 v[216:217], s[44:45], 0, v[134:135]
	s_mov_b32 m0, s39
	s_nop 0
	global_load_lds_dwordx4 v[216:217], off
	s_waitcnt vmcnt(8)
	s_waitcnt lgkmcnt(0)
	s_barrier
	s_setprio 1
	s_waitcnt lgkmcnt(0)
	v_mfma_f32_16x16x32_bf16 v[56:59], v[146:149], v[184:187], v[56:59]
	v_mfma_f32_16x16x32_bf16 v[48:51], v[158:161], v[184:187], v[48:51]
	v_mfma_f32_16x16x32_bf16 v[32:35], v[158:161], v[192:195], v[32:35]
	v_mfma_f32_16x16x32_bf16 v[40:43], v[146:149], v[192:195], v[40:43]
	v_mfma_f32_16x16x32_bf16 v[24:27], v[146:149], v[200:203], v[24:27]
	v_mfma_f32_16x16x32_bf16 v[16:19], v[158:161], v[200:203], v[16:19]
	v_mfma_f32_16x16x32_bf16 v[0:3], v[158:161], v[208:211], v[0:3]
	v_mfma_f32_16x16x32_bf16 v[8:11], v[146:149], v[208:211], v[8:11]
	v_mfma_f32_16x16x32_bf16 v[56:59], v[150:153], v[188:191], v[56:59]
	v_mfma_f32_16x16x32_bf16 v[48:51], v[162:165], v[188:191], v[48:51]
	v_mfma_f32_16x16x32_bf16 v[32:35], v[162:165], v[196:199], v[32:35]
	v_mfma_f32_16x16x32_bf16 v[40:43], v[150:153], v[196:199], v[40:43]
	v_mfma_f32_16x16x32_bf16 v[24:27], v[150:153], v[204:207], v[24:27]
	v_mfma_f32_16x16x32_bf16 v[16:19], v[162:165], v[204:207], v[16:19]
	v_mfma_f32_16x16x32_bf16 v[0:3], v[162:165], v[212:215], v[0:3]
	v_mfma_f32_16x16x32_bf16 v[8:11], v[150:153], v[212:215], v[8:11]
	s_setprio 0
	s_setprio 1
	v_mfma_f32_16x16x32_bf16 v[64:67], v[166:169], v[184:187], v[64:67]
	v_mfma_f32_16x16x32_bf16 v[52:55], v[174:177], v[184:187], v[52:55]
	v_mfma_f32_16x16x32_bf16 v[36:39], v[174:177], v[192:195], v[36:39]
	v_mfma_f32_16x16x32_bf16 v[44:47], v[166:169], v[192:195], v[44:47]
	v_mfma_f32_16x16x32_bf16 v[28:31], v[166:169], v[200:203], v[28:31]
	v_mfma_f32_16x16x32_bf16 v[20:23], v[174:177], v[200:203], v[20:23]
	v_mfma_f32_16x16x32_bf16 v[4:7], v[174:177], v[208:211], v[4:7]
	v_mfma_f32_16x16x32_bf16 v[12:15], v[166:169], v[208:211], v[12:15]
	v_mfma_f32_16x16x32_bf16 v[64:67], v[170:173], v[188:191], v[64:67]
	v_mfma_f32_16x16x32_bf16 v[52:55], v[180:183], v[188:191], v[52:55]
	v_mfma_f32_16x16x32_bf16 v[36:39], v[180:183], v[196:199], v[36:39]
	v_mfma_f32_16x16x32_bf16 v[44:47], v[170:173], v[196:199], v[44:47]
	v_mfma_f32_16x16x32_bf16 v[28:31], v[170:173], v[204:207], v[28:31]
	v_mfma_f32_16x16x32_bf16 v[20:23], v[180:183], v[204:207], v[20:23]
	v_mfma_f32_16x16x32_bf16 v[4:7], v[180:183], v[212:215], v[4:7]
	v_mfma_f32_16x16x32_bf16 v[12:15], v[170:173], v[212:215], v[12:15]
	s_setprio 0
	s_barrier
	ds_read_b128 v[146:149], v144
	ds_read_b128 v[150:153], v144 offset:1024
	ds_read_b128 v[158:161], v144 offset:2048
	ds_read_b128 v[162:165], v144 offset:3072
	ds_read_b128 v[166:169], v145
	ds_read_b128 v[170:173], v145 offset:1024
	ds_read_b128 v[174:177], v145 offset:2048
	ds_read_b128 v[180:183], v145 offset:3072
	s_add_u32 s10, s44, 0x4000
	s_addc_u32 s11, s45, 0
	s_mov_b32 m0, s46
	v_lshl_add_u64 v[216:217], s[10:11], 0, v[130:131]
	ds_read_b128 v[184:187], v156 offset:32768
	ds_read_b128 v[188:191], v156 offset:33792
	ds_read_b128 v[192:195], v156 offset:34816
	ds_read_b128 v[196:199], v156 offset:35840
	ds_read_b128 v[200:203], v156 offset:36864
	ds_read_b128 v[204:207], v156 offset:37888
	ds_read_b128 v[208:211], v156 offset:38912
	ds_read_b128 v[212:215], v156 offset:39936
	global_load_lds_dwordx4 v[216:217], off
	v_lshl_add_u64 v[216:217], s[10:11], 0, v[134:135]
	s_mov_b32 m0, s47
	s_nop 0
	global_load_lds_dwordx4 v[216:217], off
	s_waitcnt vmcnt(8)
	s_waitcnt lgkmcnt(0)
	s_barrier
	s_setprio 1
	s_waitcnt lgkmcnt(0)
	v_mfma_f32_16x16x32_bf16 v[122:125], v[146:149], v[184:187], v[122:125]
	v_mfma_f32_16x16x32_bf16 v[114:117], v[158:161], v[184:187], v[114:117]
	v_mfma_f32_16x16x32_bf16 v[98:101], v[158:161], v[192:195], v[98:101]
	v_mfma_f32_16x16x32_bf16 v[106:109], v[146:149], v[192:195], v[106:109]
	v_mfma_f32_16x16x32_bf16 v[88:91], v[146:149], v[200:203], v[88:91]
	v_mfma_f32_16x16x32_bf16 v[80:83], v[158:161], v[200:203], v[80:83]
	v_mfma_f32_16x16x32_bf16 v[60:63], v[158:161], v[208:211], v[60:63]
	v_mfma_f32_16x16x32_bf16 v[72:75], v[146:149], v[208:211], v[72:75]
	v_mfma_f32_16x16x32_bf16 v[122:125], v[150:153], v[188:191], v[122:125]
	v_mfma_f32_16x16x32_bf16 v[114:117], v[162:165], v[188:191], v[114:117]
	v_mfma_f32_16x16x32_bf16 v[98:101], v[162:165], v[196:199], v[98:101]
	v_mfma_f32_16x16x32_bf16 v[106:109], v[150:153], v[196:199], v[106:109]
	v_mfma_f32_16x16x32_bf16 v[88:91], v[150:153], v[204:207], v[88:91]
	v_mfma_f32_16x16x32_bf16 v[80:83], v[162:165], v[204:207], v[80:83]
	v_mfma_f32_16x16x32_bf16 v[60:63], v[162:165], v[212:215], v[60:63]
	v_mfma_f32_16x16x32_bf16 v[72:75], v[150:153], v[212:215], v[72:75]
	s_setprio 0
	s_setprio 1
	v_mfma_f32_16x16x32_bf16 v[126:129], v[166:169], v[184:187], v[126:129]
	v_mfma_f32_16x16x32_bf16 v[118:121], v[174:177], v[184:187], v[118:121]
	v_mfma_f32_16x16x32_bf16 v[102:105], v[174:177], v[192:195], v[102:105]
	v_mfma_f32_16x16x32_bf16 v[110:113], v[166:169], v[192:195], v[110:113]
	v_mfma_f32_16x16x32_bf16 v[92:95], v[166:169], v[200:203], v[92:95]
	v_mfma_f32_16x16x32_bf16 v[84:87], v[174:177], v[200:203], v[84:87]
	v_mfma_f32_16x16x32_bf16 v[68:71], v[174:177], v[208:211], v[68:71]
	v_mfma_f32_16x16x32_bf16 v[76:79], v[166:169], v[208:211], v[76:79]
	v_mfma_f32_16x16x32_bf16 v[126:129], v[170:173], v[188:191], v[126:129]
	v_mfma_f32_16x16x32_bf16 v[118:121], v[180:183], v[188:191], v[118:121]
	v_mfma_f32_16x16x32_bf16 v[102:105], v[180:183], v[196:199], v[102:105]
	v_mfma_f32_16x16x32_bf16 v[110:113], v[170:173], v[196:199], v[110:113]
	v_mfma_f32_16x16x32_bf16 v[92:95], v[170:173], v[204:207], v[92:95]
	v_mfma_f32_16x16x32_bf16 v[84:87], v[180:183], v[204:207], v[84:87]
	v_mfma_f32_16x16x32_bf16 v[68:71], v[180:183], v[212:215], v[68:71]
	v_mfma_f32_16x16x32_bf16 v[76:79], v[170:173], v[212:215], v[76:79]
	s_setprio 0
	s_barrier
; #define PG8_BAR __builtin_amdgcn_s_barrier()
; template <class Epi, class Sched, bool ALIGN_EPI = false, bool SP2 = false>
; __device__ __forceinline__ void gemm_phase(PG8_LAS unsigned char* lds, const Gemm g, const Sched& S, const Epi& E) {
;     ...
;         if constexpr (Epi::PEEL) {
;             const char* a1 = cA + kstepA; const char* a2 = cA + 2 * kstepA; const char* b2 = cB + 2 * kstepB; const char* a3 = a2 + kstepA; const char* b3 = b2 + kstepB;
;             PG8_ITER(8);
;         }
;         for (int t = (Epi::PEEL ? 2 : 0); t < nt; t += 2) {
;             const bool last = (t == nt - 2);
;             const char* a1 = cA + (size_t)(t + 1) * kstepA;
;             const char* a2 = last ? nA : cA + (size_t)(t + 2) * kstepA; const char* b2 = last ? nB : cB + (size_t)(t + 2) * kstepB;
;             const char* a3 = a2 + kstepA; const char* b3 = b2 + kstepB;
;             PG8_ITER(8);
;         }
;     ...
;         if constexpr (ALIGN_EPI) { if (wr == 0) PG8_BAR; }
	s_mov_b32 m0, s99
	v_lshl_add_u64 v[154:155], v[154:155], 0, s[36:37]
	s_add_u32 s10, s42, 0x40080
	ds_read_b128 v[184:187], v156 offset:49152
	ds_read_b128 v[188:191], v156 offset:50176
	ds_read_b128 v[192:195], v156 offset:51200
	ds_read_b128 v[196:199], v156 offset:52224
	ds_read_b128 v[200:203], v156 offset:53248
	ds_read_b128 v[204:207], v156 offset:54272
	ds_read_b128 v[208:211], v156 offset:55296
	ds_read_b128 v[212:215], v156 offset:56320
	global_load_lds_dwordx4 v[154:155], off
	v_lshl_add_u64 v[154:155], v[178:179], 0, s[36:37]
	s_mov_b32 m0, vcc_lo
	s_addc_u32 s11, s43, 0
	global_load_lds_dwordx4 v[154:155], off
	v_lshl_add_u64 v[154:155], s[10:11], 0, v[132:133]
	s_mov_b32 m0, vcc_hi
	s_nop 0
	global_load_lds_dwordx4 v[154:155], off
	v_lshl_add_u64 v[154:155], s[10:11], 0, v[136:137]
	s_mov_b32 m0, s38
	s_nop 0
	global_load_lds_dwordx4 v[154:155], off
	v_lshl_add_u64 v[154:155], s[34:35], 0, v[130:131]
	s_mov_b32 m0, s49
	s_nop 0
	global_load_lds_dwordx4 v[154:155], off
	v_lshl_add_u64 v[154:155], s[34:35], 0, v[134:135]
	s_mov_b32 m0, s50
	s_nop 0
	global_load_lds_dwordx4 v[154:155], off
	s_waitcnt vmcnt(8)
	s_waitcnt lgkmcnt(0)
	s_barrier
	s_setprio 1
	s_waitcnt lgkmcnt(0)
	v_mfma_f32_16x16x32_bf16 v[56:59], v[146:149], v[184:187], v[56:59]
	v_mfma_f32_16x16x32_bf16 v[48:51], v[158:161], v[184:187], v[48:51]
	v_mfma_f32_16x16x32_bf16 v[32:35], v[158:161], v[192:195], v[32:35]
	v_mfma_f32_16x16x32_bf16 v[40:43], v[146:149], v[192:195], v[40:43]
	v_mfma_f32_16x16x32_bf16 v[24:27], v[146:149], v[200:203], v[24:27]
	v_mfma_f32_16x16x32_bf16 v[16:19], v[158:161], v[200:203], v[16:19]
	v_mfma_f32_16x16x32_bf16 v[0:3], v[158:161], v[208:211], v[0:3]
	v_mfma_f32_16x16x32_bf16 v[8:11], v[146:149], v[208:211], v[8:11]
	v_mfma_f32_16x16x32_bf16 v[56:59], v[150:153], v[188:191], v[56:59]
	v_mfma_f32_16x16x32_bf16 v[48:51], v[162:165], v[188:191], v[48:51]
	v_mfma_f32_16x16x32_bf16 v[32:35], v[162:165], v[196:199], v[32:35]
	v_mfma_f32_16x16x32_bf16 v[40:43], v[150:153], v[196:199], v[40:43]
	v_mfma_f32_16x16x32_bf16 v[24:27], v[150:153], v[204:207], v[24:27]
	v_mfma_f32_16x16x32_bf16 v[16:19], v[162:165], v[204:207], v[16:19]
	v_mfma_f32_16x16x32_bf16 v[0:3], v[162:165], v[212:215], v[0:3]
	v_mfma_f32_16x16x32_bf16 v[8:11], v[150:153], v[212:215], v[8:11]
	s_setprio 0
	s_setprio 1
	v_mfma_f32_16x16x32_bf16 v[64:67], v[166:169], v[184:187], v[64:67]
	v_mfma_f32_16x16x32_bf16 v[52:55], v[174:177], v[184:187], v[52:55]
	v_mfma_f32_16x16x32_bf16 v[36:39], v[174:177], v[192:195], v[36:39]
	v_mfma_f32_16x16x32_bf16 v[44:47], v[166:169], v[192:195], v[44:47]
	v_mfma_f32_16x16x32_bf16 v[28:31], v[166:169], v[200:203], v[28:31]
	v_mfma_f32_16x16x32_bf16 v[20:23], v[174:177], v[200:203], v[20:23]
	v_mfma_f32_16x16x32_bf16 v[4:7], v[174:177], v[208:211], v[4:7]
	v_mfma_f32_16x16x32_bf16 v[12:15], v[166:169], v[208:211], v[12:15]
	v_mfma_f32_16x16x32_bf16 v[64:67], v[170:173], v[188:191], v[64:67]
	v_mfma_f32_16x16x32_bf16 v[52:55], v[180:183], v[188:191], v[52:55]
	v_mfma_f32_16x16x32_bf16 v[36:39], v[180:183], v[196:199], v[36:39]
	v_mfma_f32_16x16x32_bf16 v[44:47], v[170:173], v[196:199], v[44:47]
	v_mfma_f32_16x16x32_bf16 v[28:31], v[170:173], v[204:207], v[28:31]
	v_mfma_f32_16x16x32_bf16 v[20:23], v[180:183], v[204:207], v[20:23]
	v_mfma_f32_16x16x32_bf16 v[4:7], v[180:183], v[212:215], v[4:7]
	v_mfma_f32_16x16x32_bf16 v[12:15], v[170:173], v[212:215], v[12:15]
	s_setprio 0
	s_barrier
	s_add_i32 s18, s18, 2
	s_add_u32 s3, s3, 0x100
	s_addc_u32 s2, s2, 0
	s_add_u32 s0, s0, 0x800000
	s_addc_u32 s1, s1, 0
	s_cmp_gt_u32 s18, 13
	s_cbranch_scc0 .LBB0_478
	s_and_b64 vcc, exec, s[16:17]
	s_cbranch_vccz .LBB0_481
	s_barrier
